# combo7 + attention output epilogue: lane swap via DPP quad_perm instead of ds_swizzle round trips
# speedup vs baseline: 1.0034x; 1.0010x over previous
.LBB0_469:
	v_cmp_gt_u32_e32 vcc, 32, v177
	s_and_saveexec_b64 s[8:9], vcc
	ds_write_b32 v178, v0
	s_or_b64 exec, exec, s[8:9]
	s_lshl_b64 s[8:9], s[14:15], 12
	s_add_u32 s8, s22, s8
	s_waitcnt lgkmcnt(0)
	s_addc_u32 s9, s23, s9
	s_lshl_b32 s10, s20, 1
	ds_read_b128 v[36:39], v171
	ds_read_b128 v[10:13], v171 offset:32
	s_add_u32 s8, s8, s10
	s_addc_u32 s9, s9, 0
	v_readlane_b32 s10, v255, 0
	s_add_u32 s10, s8, s10
	s_waitcnt lgkmcnt(1)
	v_rcp_f32_e32 v32, v36
	s_addc_u32 s11, s9, 0
	s_lshl_b64 s[8:9], s[74:75], 1
	s_add_u32 s10, s10, s8
	v_and_b32_e32 v0, 1, v174
	s_addc_u32 s11, s11, s9
	v_cmp_eq_u32_e64 s[8:9], 0, v0
	v_lshlrev_b32_e32 v0, 1, v176
	v_lshl_add_u64 v[14:15], s[10:11], 0, v[0:1]
	v_lshlrev_b32_e32 v0, 14, v175
	v_lshl_add_u64 v[14:15], v[14:15], 0, v[0:1]
	v_mul_f32_e32 v0, v82, v32
	ds_read_b128 v[6:9], v171 offset:64
	ds_read_b128 v[2:5], v171 offset:96
	s_nop 1
	v_mov_b32_dpp v33, v0 quad_perm:[1,0,3,2] row_mask:0xf bank_mask:0xf
	s_and_saveexec_b64 s[10:11], s[8:9]
	s_cbranch_execz .LBB0_473
	s_waitcnt lgkmcnt(0)
	v_cvt_pk_bf16_f32 v0, v0, v33
	global_store_dword v[14:15], v0, off
.LBB0_473:
	s_or_b64 exec, exec, s[10:11]
	v_mul_f32_e32 v0, v66, v32
	s_waitcnt lgkmcnt(0)
	s_nop 1
	v_mov_b32_dpp v33, v0 quad_perm:[1,0,3,2] row_mask:0xf bank_mask:0xf
	s_and_saveexec_b64 s[10:11], s[8:9]
	s_cbranch_execz .LBB0_475
	s_waitcnt lgkmcnt(0)
	v_cvt_pk_bf16_f32 v0, v0, v33
	global_store_dword v[14:15], v0, off offset:64
.LBB0_475:
	s_or_b64 exec, exec, s[10:11]
	v_mul_f32_e32 v0, v50, v32
	s_waitcnt lgkmcnt(0)
	s_nop 1
	v_mov_b32_dpp v33, v0 quad_perm:[1,0,3,2] row_mask:0xf bank_mask:0xf
	s_and_saveexec_b64 s[10:11], s[8:9]
	s_cbranch_execz .LBB0_477
	s_waitcnt lgkmcnt(0)
	v_cvt_pk_bf16_f32 v0, v0, v33
	global_store_dword v[14:15], v0, off offset:128
.LBB0_477:
	s_or_b64 exec, exec, s[10:11]
	v_mul_f32_e32 v0, v16, v32
	s_nop 1
	v_mov_b32_dpp v16, v0 quad_perm:[1,0,3,2] row_mask:0xf bank_mask:0xf
	s_and_saveexec_b64 s[10:11], s[8:9]
	s_cbranch_execz .LBB0_479
	s_waitcnt lgkmcnt(0)
	v_cvt_pk_bf16_f32 v0, v0, v16
	global_store_dword v[14:15], v0, off offset:192
.LBB0_479:
	s_or_b64 exec, exec, s[10:11]
	v_rcp_f32_e32 v0, v37
	s_waitcnt lgkmcnt(0)
	v_mul_f32_e32 v16, v83, v0
	s_nop 1
	v_mov_b32_dpp v32, v16 quad_perm:[1,0,3,2] row_mask:0xf bank_mask:0xf
	s_and_saveexec_b64 s[10:11], s[8:9]
	s_cbranch_execz .LBB0_481
	s_waitcnt lgkmcnt(0)
	v_cvt_pk_bf16_f32 v16, v16, v32
	v_add_co_u32_e32 v32, vcc, 0x1000, v14
	s_nop 1
	v_addc_co_u32_e32 v33, vcc, 0, v15, vcc
	global_store_dword v[32:33], v16, off
.LBB0_481:
	s_or_b64 exec, exec, s[10:11]
	v_mul_f32_e32 v16, v67, v0
	s_waitcnt lgkmcnt(0)
	s_nop 1
	v_mov_b32_dpp v32, v16 quad_perm:[1,0,3,2] row_mask:0xf bank_mask:0xf
	s_and_saveexec_b64 s[10:11], s[8:9]
	s_cbranch_execz .LBB0_483
	s_waitcnt lgkmcnt(0)
	v_cvt_pk_bf16_f32 v16, v16, v32
	v_add_co_u32_e32 v32, vcc, 0x1000, v14
	s_nop 1
	v_addc_co_u32_e32 v33, vcc, 0, v15, vcc
	global_store_dword v[32:33], v16, off offset:64
.LBB0_483:
	s_or_b64 exec, exec, s[10:11]
	v_mul_f32_e32 v16, v51, v0
	s_waitcnt lgkmcnt(0)
	s_nop 1
	v_mov_b32_dpp v32, v16 quad_perm:[1,0,3,2] row_mask:0xf bank_mask:0xf
	s_and_saveexec_b64 s[10:11], s[8:9]
	s_cbranch_execz .LBB0_485
	s_waitcnt lgkmcnt(0)
	v_cvt_pk_bf16_f32 v16, v16, v32
	v_add_co_u32_e32 v32, vcc, 0x1000, v14
	s_nop 1
	v_addc_co_u32_e32 v33, vcc, 0, v15, vcc
	global_store_dword v[32:33], v16, off offset:128
.LBB0_485:
	s_or_b64 exec, exec, s[10:11]
	v_mul_f32_e32 v0, v17, v0
	s_nop 1
	v_mov_b32_dpp v16, v0 quad_perm:[1,0,3,2] row_mask:0xf bank_mask:0xf
	s_and_saveexec_b64 s[10:11], s[8:9]
	s_cbranch_execz .LBB0_487
	s_waitcnt lgkmcnt(0)
	v_cvt_pk_bf16_f32 v0, v0, v16
	v_add_co_u32_e32 v16, vcc, 0x1000, v14
	s_nop 1
	v_addc_co_u32_e32 v17, vcc, 0, v15, vcc
	global_store_dword v[16:17], v0, off offset:192
.LBB0_487:
	s_or_b64 exec, exec, s[10:11]
	v_rcp_f32_e32 v0, v38
	s_waitcnt lgkmcnt(0)
	v_mul_f32_e32 v16, v84, v0
	s_nop 1
	v_mov_b32_dpp v17, v16 quad_perm:[1,0,3,2] row_mask:0xf bank_mask:0xf
	s_and_saveexec_b64 s[10:11], s[8:9]
	s_cbranch_execz .LBB0_489
	s_waitcnt lgkmcnt(0)
	v_cvt_pk_bf16_f32 v32, v16, v17
	v_add_co_u32_e32 v16, vcc, 0x2000, v14
	s_nop 1
	v_addc_co_u32_e32 v17, vcc, 0, v15, vcc
	global_store_dword v[16:17], v32, off
.LBB0_489:
	s_or_b64 exec, exec, s[10:11]
	v_mul_f32_e32 v16, v68, v0
	s_waitcnt lgkmcnt(0)
	s_nop 1
	v_mov_b32_dpp v17, v16 quad_perm:[1,0,3,2] row_mask:0xf bank_mask:0xf
	s_and_saveexec_b64 s[10:11], s[8:9]
	s_cbranch_execz .LBB0_491
	s_waitcnt lgkmcnt(0)
	v_cvt_pk_bf16_f32 v32, v16, v17
	v_add_co_u32_e32 v16, vcc, 0x2000, v14
	s_nop 1
	v_addc_co_u32_e32 v17, vcc, 0, v15, vcc
	global_store_dword v[16:17], v32, off offset:64
.LBB0_491:
	s_or_b64 exec, exec, s[10:11]
	v_mul_f32_e32 v16, v52, v0
	s_waitcnt lgkmcnt(0)
	s_nop 1
	v_mov_b32_dpp v17, v16 quad_perm:[1,0,3,2] row_mask:0xf bank_mask:0xf
	s_and_saveexec_b64 s[10:11], s[8:9]
	s_cbranch_execz .LBB0_493
	s_waitcnt lgkmcnt(0)
	v_cvt_pk_bf16_f32 v32, v16, v17
	v_add_co_u32_e32 v16, vcc, 0x2000, v14
	s_nop 1
	v_addc_co_u32_e32 v17, vcc, 0, v15, vcc
	global_store_dword v[16:17], v32, off offset:128
.LBB0_493:
	s_or_b64 exec, exec, s[10:11]
	v_mul_f32_e32 v0, v18, v0
	s_nop 1
	v_mov_b32_dpp v16, v0 quad_perm:[1,0,3,2] row_mask:0xf bank_mask:0xf
	s_and_saveexec_b64 s[10:11], s[8:9]
	s_cbranch_execz .LBB0_495
	s_waitcnt lgkmcnt(0)
	v_cvt_pk_bf16_f32 v0, v0, v16
	v_add_co_u32_e32 v16, vcc, 0x2000, v14
	s_nop 1
	v_addc_co_u32_e32 v17, vcc, 0, v15, vcc
	global_store_dword v[16:17], v0, off offset:192
.LBB0_495:
	s_or_b64 exec, exec, s[10:11]
	v_rcp_f32_e32 v0, v39
	s_waitcnt lgkmcnt(0)
	v_mul_f32_e32 v16, v85, v0
	s_nop 1
	v_mov_b32_dpp v17, v16 quad_perm:[1,0,3,2] row_mask:0xf bank_mask:0xf
	s_and_saveexec_b64 s[10:11], s[8:9]
	s_cbranch_execz .LBB0_497
	s_waitcnt lgkmcnt(0)
	v_cvt_pk_bf16_f32 v18, v16, v17
	v_add_co_u32_e32 v16, vcc, 0x3000, v14
	s_nop 1
	v_addc_co_u32_e32 v17, vcc, 0, v15, vcc
	global_store_dword v[16:17], v18, off
.LBB0_497:
	s_or_b64 exec, exec, s[10:11]
	v_mul_f32_e32 v16, v69, v0
	s_waitcnt lgkmcnt(0)
	s_nop 1
	v_mov_b32_dpp v17, v16 quad_perm:[1,0,3,2] row_mask:0xf bank_mask:0xf
	s_and_saveexec_b64 s[10:11], s[8:9]
	s_cbranch_execz .LBB0_499
	s_waitcnt lgkmcnt(0)
	v_cvt_pk_bf16_f32 v18, v16, v17
	v_add_co_u32_e32 v16, vcc, 0x3000, v14
	s_nop 1
	v_addc_co_u32_e32 v17, vcc, 0, v15, vcc
	global_store_dword v[16:17], v18, off offset:64
.LBB0_499:
	s_or_b64 exec, exec, s[10:11]
	v_mul_f32_e32 v16, v53, v0
	s_waitcnt lgkmcnt(0)
	s_nop 1
	v_mov_b32_dpp v17, v16 quad_perm:[1,0,3,2] row_mask:0xf bank_mask:0xf
	s_and_saveexec_b64 s[10:11], s[8:9]
	s_cbranch_execz .LBB0_501
	s_waitcnt lgkmcnt(0)
	v_cvt_pk_bf16_f32 v18, v16, v17
	v_add_co_u32_e32 v16, vcc, 0x3000, v14
	s_nop 1
	v_addc_co_u32_e32 v17, vcc, 0, v15, vcc
	global_store_dword v[16:17], v18, off offset:128
.LBB0_501:
	s_or_b64 exec, exec, s[10:11]
	v_mul_f32_e32 v0, v19, v0
	s_nop 1
	v_mov_b32_dpp v16, v0 quad_perm:[1,0,3,2] row_mask:0xf bank_mask:0xf
	s_and_saveexec_b64 s[10:11], s[8:9]
	s_cbranch_execz .LBB0_503
	s_waitcnt lgkmcnt(0)
	v_cvt_pk_bf16_f32 v0, v0, v16
	v_add_co_u32_e32 v16, vcc, 0x3000, v14
	s_nop 1
	v_addc_co_u32_e32 v17, vcc, 0, v15, vcc
	global_store_dword v[16:17], v0, off offset:192
.LBB0_503:
	s_or_b64 exec, exec, s[10:11]
	v_rcp_f32_e32 v0, v10
	s_nop 0
	v_mul_f32_e32 v10, v86, v0
	s_waitcnt lgkmcnt(0)
	s_nop 1
	v_mov_b32_dpp v16, v10 quad_perm:[1,0,3,2] row_mask:0xf bank_mask:0xf
	s_and_saveexec_b64 s[10:11], s[8:9]
	s_cbranch_execz .LBB0_505
	s_waitcnt lgkmcnt(0)
	v_cvt_pk_bf16_f32 v10, v10, v16
	v_add_co_u32_e32 v16, vcc, 0x8000, v14
	s_nop 1
	v_addc_co_u32_e32 v17, vcc, 0, v15, vcc
	global_store_dword v[16:17], v10, off
.LBB0_505:
	s_or_b64 exec, exec, s[10:11]
	v_mul_f32_e32 v10, v70, v0
	s_waitcnt lgkmcnt(0)
	s_nop 1
	v_mov_b32_dpp v16, v10 quad_perm:[1,0,3,2] row_mask:0xf bank_mask:0xf
	s_and_saveexec_b64 s[10:11], s[8:9]
	s_cbranch_execz .LBB0_507
	s_waitcnt lgkmcnt(0)
	v_cvt_pk_bf16_f32 v10, v10, v16
	v_add_co_u32_e32 v16, vcc, 0x8000, v14
	s_nop 1
	v_addc_co_u32_e32 v17, vcc, 0, v15, vcc
	global_store_dword v[16:17], v10, off offset:64
.LBB0_507:
	s_or_b64 exec, exec, s[10:11]
	v_mul_f32_e32 v10, v54, v0
	s_waitcnt lgkmcnt(0)
	s_nop 1
	v_mov_b32_dpp v16, v10 quad_perm:[1,0,3,2] row_mask:0xf bank_mask:0xf
	s_and_saveexec_b64 s[10:11], s[8:9]
	s_cbranch_execz .LBB0_509
	s_waitcnt lgkmcnt(0)
	v_cvt_pk_bf16_f32 v10, v10, v16
	v_add_co_u32_e32 v16, vcc, 0x8000, v14
	s_nop 1
	v_addc_co_u32_e32 v17, vcc, 0, v15, vcc
	global_store_dword v[16:17], v10, off offset:128
.LBB0_509:
	s_or_b64 exec, exec, s[10:11]
	v_mul_f32_e32 v0, v20, v0
	s_nop 1
	v_mov_b32_dpp v10, v0 quad_perm:[1,0,3,2] row_mask:0xf bank_mask:0xf
	s_and_saveexec_b64 s[10:11], s[8:9]
	s_cbranch_execz .LBB0_511
	s_waitcnt lgkmcnt(1)
	v_add_co_u32_e32 v16, vcc, 0x8000, v14
	s_waitcnt lgkmcnt(0)
	v_cvt_pk_bf16_f32 v0, v0, v10
	s_nop 0
	v_addc_co_u32_e32 v17, vcc, 0, v15, vcc
	global_store_dword v[16:17], v0, off offset:192
.LBB0_511:
	s_or_b64 exec, exec, s[10:11]
	v_rcp_f32_e32 v0, v11
	s_waitcnt lgkmcnt(0)
	v_mul_f32_e32 v10, v87, v0
	s_nop 1
	v_mov_b32_dpp v11, v10 quad_perm:[1,0,3,2] row_mask:0xf bank_mask:0xf
	s_and_saveexec_b64 s[10:11], s[8:9]
	s_cbranch_execz .LBB0_513
	s_waitcnt lgkmcnt(0)
	v_cvt_pk_bf16_f32 v16, v10, v11
	v_add_co_u32_e32 v10, vcc, 0x9000, v14
	s_nop 1
	v_addc_co_u32_e32 v11, vcc, 0, v15, vcc
	global_store_dword v[10:11], v16, off
.LBB0_513:
	s_or_b64 exec, exec, s[10:11]
	v_mul_f32_e32 v10, v71, v0
	s_waitcnt lgkmcnt(0)
	s_nop 1
	v_mov_b32_dpp v11, v10 quad_perm:[1,0,3,2] row_mask:0xf bank_mask:0xf
	s_and_saveexec_b64 s[10:11], s[8:9]
	s_cbranch_execz .LBB0_515
	s_waitcnt lgkmcnt(0)
	v_cvt_pk_bf16_f32 v16, v10, v11
	v_add_co_u32_e32 v10, vcc, 0x9000, v14
	s_nop 1
	v_addc_co_u32_e32 v11, vcc, 0, v15, vcc
	global_store_dword v[10:11], v16, off offset:64
.LBB0_515:
	s_or_b64 exec, exec, s[10:11]
	v_mul_f32_e32 v10, v55, v0
	s_waitcnt lgkmcnt(0)
	s_nop 1
	v_mov_b32_dpp v11, v10 quad_perm:[1,0,3,2] row_mask:0xf bank_mask:0xf
	s_and_saveexec_b64 s[10:11], s[8:9]
	s_cbranch_execz .LBB0_517
	s_waitcnt lgkmcnt(0)
	v_cvt_pk_bf16_f32 v16, v10, v11
	v_add_co_u32_e32 v10, vcc, 0x9000, v14
	s_nop 1
	v_addc_co_u32_e32 v11, vcc, 0, v15, vcc
	global_store_dword v[10:11], v16, off offset:128
.LBB0_517:
	s_or_b64 exec, exec, s[10:11]
	v_mul_f32_e32 v0, v21, v0
	s_nop 1
	v_mov_b32_dpp v10, v0 quad_perm:[1,0,3,2] row_mask:0xf bank_mask:0xf
	s_and_saveexec_b64 s[10:11], s[8:9]
	s_cbranch_execz .LBB0_519
	s_waitcnt lgkmcnt(0)
	v_cvt_pk_bf16_f32 v0, v0, v10
	v_add_co_u32_e32 v10, vcc, 0x9000, v14
	s_nop 1
	v_addc_co_u32_e32 v11, vcc, 0, v15, vcc
	global_store_dword v[10:11], v0, off offset:192
.LBB0_519:
	s_or_b64 exec, exec, s[10:11]
	v_rcp_f32_e32 v0, v12
	s_waitcnt lgkmcnt(0)
	v_mul_f32_e32 v10, v88, v0
	s_nop 1
	v_mov_b32_dpp v11, v10 quad_perm:[1,0,3,2] row_mask:0xf bank_mask:0xf
	s_and_saveexec_b64 s[10:11], s[8:9]
	s_cbranch_execz .LBB0_521
	s_waitcnt lgkmcnt(0)
	v_cvt_pk_bf16_f32 v12, v10, v11
	v_add_co_u32_e32 v10, vcc, 0xa000, v14
	s_nop 1
	v_addc_co_u32_e32 v11, vcc, 0, v15, vcc
	global_store_dword v[10:11], v12, off
.LBB0_521:
	s_or_b64 exec, exec, s[10:11]
	v_mul_f32_e32 v10, v72, v0
	s_waitcnt lgkmcnt(0)
	s_nop 1
	v_mov_b32_dpp v11, v10 quad_perm:[1,0,3,2] row_mask:0xf bank_mask:0xf
	s_and_saveexec_b64 s[10:11], s[8:9]
	s_cbranch_execz .LBB0_523
	s_waitcnt lgkmcnt(0)
	v_cvt_pk_bf16_f32 v12, v10, v11
	v_add_co_u32_e32 v10, vcc, 0xa000, v14
	s_nop 1
	v_addc_co_u32_e32 v11, vcc, 0, v15, vcc
	global_store_dword v[10:11], v12, off offset:64
.LBB0_523:
	s_or_b64 exec, exec, s[10:11]
	v_mul_f32_e32 v10, v56, v0
	s_waitcnt lgkmcnt(0)
	s_nop 1
	v_mov_b32_dpp v11, v10 quad_perm:[1,0,3,2] row_mask:0xf bank_mask:0xf
	s_and_saveexec_b64 s[10:11], s[8:9]
	s_cbranch_execz .LBB0_525
	s_waitcnt lgkmcnt(0)
	v_cvt_pk_bf16_f32 v12, v10, v11
	v_add_co_u32_e32 v10, vcc, 0xa000, v14
	s_nop 1
	v_addc_co_u32_e32 v11, vcc, 0, v15, vcc
	global_store_dword v[10:11], v12, off offset:128
.LBB0_525:
	s_or_b64 exec, exec, s[10:11]
	v_mul_f32_e32 v0, v22, v0
	s_nop 1
	v_mov_b32_dpp v10, v0 quad_perm:[1,0,3,2] row_mask:0xf bank_mask:0xf
	s_and_saveexec_b64 s[10:11], s[8:9]
	s_cbranch_execz .LBB0_527
	s_waitcnt lgkmcnt(0)
	v_cvt_pk_bf16_f32 v0, v0, v10
	v_add_co_u32_e32 v10, vcc, 0xa000, v14
	s_nop 1
	v_addc_co_u32_e32 v11, vcc, 0, v15, vcc
	global_store_dword v[10:11], v0, off offset:192
.LBB0_527:
	s_or_b64 exec, exec, s[10:11]
	v_rcp_f32_e32 v0, v13
	s_waitcnt lgkmcnt(0)
	v_mul_f32_e32 v10, v89, v0
	s_nop 1
	v_mov_b32_dpp v11, v10 quad_perm:[1,0,3,2] row_mask:0xf bank_mask:0xf
	s_and_saveexec_b64 s[10:11], s[8:9]
	s_cbranch_execz .LBB0_529
	s_waitcnt lgkmcnt(0)
	v_cvt_pk_bf16_f32 v12, v10, v11
	v_add_co_u32_e32 v10, vcc, 0xb000, v14
	s_nop 1
	v_addc_co_u32_e32 v11, vcc, 0, v15, vcc
	global_store_dword v[10:11], v12, off
.LBB0_529:
	s_or_b64 exec, exec, s[10:11]
	v_mul_f32_e32 v10, v73, v0
	s_waitcnt lgkmcnt(0)
	s_nop 1
	v_mov_b32_dpp v11, v10 quad_perm:[1,0,3,2] row_mask:0xf bank_mask:0xf
	s_and_saveexec_b64 s[10:11], s[8:9]
	s_cbranch_execz .LBB0_531
	s_waitcnt lgkmcnt(0)
	v_cvt_pk_bf16_f32 v12, v10, v11
	v_add_co_u32_e32 v10, vcc, 0xb000, v14
	s_nop 1
	v_addc_co_u32_e32 v11, vcc, 0, v15, vcc
	global_store_dword v[10:11], v12, off offset:64
.LBB0_531:
	s_or_b64 exec, exec, s[10:11]
	v_mul_f32_e32 v10, v57, v0
	s_waitcnt lgkmcnt(0)
	s_nop 1
	v_mov_b32_dpp v11, v10 quad_perm:[1,0,3,2] row_mask:0xf bank_mask:0xf
	s_and_saveexec_b64 s[10:11], s[8:9]
	s_cbranch_execz .LBB0_533
	s_waitcnt lgkmcnt(0)
	v_cvt_pk_bf16_f32 v12, v10, v11
	v_add_co_u32_e32 v10, vcc, 0xb000, v14
	s_nop 1
	v_addc_co_u32_e32 v11, vcc, 0, v15, vcc
	global_store_dword v[10:11], v12, off offset:128
.LBB0_533:
	s_or_b64 exec, exec, s[10:11]
	v_mul_f32_e32 v0, v23, v0
	s_nop 1
	v_mov_b32_dpp v10, v0 quad_perm:[1,0,3,2] row_mask:0xf bank_mask:0xf
	s_and_saveexec_b64 s[10:11], s[8:9]
	s_cbranch_execz .LBB0_535
	s_waitcnt lgkmcnt(0)
	v_cvt_pk_bf16_f32 v0, v0, v10
	v_add_co_u32_e32 v10, vcc, 0xb000, v14
	s_nop 1
	v_addc_co_u32_e32 v11, vcc, 0, v15, vcc
	global_store_dword v[10:11], v0, off offset:192
.LBB0_535:
	s_or_b64 exec, exec, s[10:11]
	v_rcp_f32_e32 v0, v6
	s_nop 0
	v_mul_f32_e32 v6, v90, v0
	s_waitcnt lgkmcnt(0)
	s_nop 1
	v_mov_b32_dpp v10, v6 quad_perm:[1,0,3,2] row_mask:0xf bank_mask:0xf
	s_and_saveexec_b64 s[10:11], s[8:9]
	s_cbranch_execz .LBB0_537
	s_waitcnt lgkmcnt(0)
	v_cvt_pk_bf16_f32 v6, v6, v10
	v_add_co_u32_e32 v10, vcc, 0x10000, v14
	s_nop 1
	v_addc_co_u32_e32 v11, vcc, 0, v15, vcc
	global_store_dword v[10:11], v6, off
.LBB0_537:
	s_or_b64 exec, exec, s[10:11]
	v_mul_f32_e32 v6, v74, v0
	s_waitcnt lgkmcnt(0)
	s_nop 1
	v_mov_b32_dpp v10, v6 quad_perm:[1,0,3,2] row_mask:0xf bank_mask:0xf
	s_and_saveexec_b64 s[10:11], s[8:9]
	s_cbranch_execz .LBB0_539
	s_waitcnt lgkmcnt(0)
	v_cvt_pk_bf16_f32 v6, v6, v10
	v_add_co_u32_e32 v10, vcc, 0x10000, v14
	s_nop 1
	v_addc_co_u32_e32 v11, vcc, 0, v15, vcc
	global_store_dword v[10:11], v6, off offset:64
.LBB0_539:
	s_or_b64 exec, exec, s[10:11]
	v_mul_f32_e32 v6, v58, v0
	s_waitcnt lgkmcnt(0)
	s_nop 1
	v_mov_b32_dpp v10, v6 quad_perm:[1,0,3,2] row_mask:0xf bank_mask:0xf
	s_and_saveexec_b64 s[10:11], s[8:9]
	s_cbranch_execz .LBB0_541
	s_waitcnt lgkmcnt(0)
	v_cvt_pk_bf16_f32 v6, v6, v10
	v_add_co_u32_e32 v10, vcc, 0x10000, v14
	s_nop 1
	v_addc_co_u32_e32 v11, vcc, 0, v15, vcc
	global_store_dword v[10:11], v6, off offset:128
.LBB0_541:
	s_or_b64 exec, exec, s[10:11]
	v_mul_f32_e32 v0, v24, v0
	s_nop 1
	v_mov_b32_dpp v6, v0 quad_perm:[1,0,3,2] row_mask:0xf bank_mask:0xf
	s_and_saveexec_b64 s[10:11], s[8:9]
	s_cbranch_execz .LBB0_543
	s_waitcnt lgkmcnt(1)
	v_add_co_u32_e32 v10, vcc, 0x10000, v14
	s_waitcnt lgkmcnt(0)
	v_cvt_pk_bf16_f32 v0, v0, v6
	s_nop 0
	v_addc_co_u32_e32 v11, vcc, 0, v15, vcc
	global_store_dword v[10:11], v0, off offset:192
.LBB0_543:
	s_or_b64 exec, exec, s[10:11]
	v_rcp_f32_e32 v0, v7
	s_waitcnt lgkmcnt(0)
	v_mul_f32_e32 v6, v91, v0
	s_nop 1
	v_mov_b32_dpp v7, v6 quad_perm:[1,0,3,2] row_mask:0xf bank_mask:0xf
	s_and_saveexec_b64 s[10:11], s[8:9]
	s_cbranch_execz .LBB0_545
	s_waitcnt lgkmcnt(0)
	v_cvt_pk_bf16_f32 v10, v6, v7
	v_add_co_u32_e32 v6, vcc, 0x11000, v14
	s_nop 1
	v_addc_co_u32_e32 v7, vcc, 0, v15, vcc
	global_store_dword v[6:7], v10, off
.LBB0_545:
	s_or_b64 exec, exec, s[10:11]
	v_mul_f32_e32 v6, v75, v0
	s_waitcnt lgkmcnt(0)
	s_nop 1
	v_mov_b32_dpp v7, v6 quad_perm:[1,0,3,2] row_mask:0xf bank_mask:0xf
	s_and_saveexec_b64 s[10:11], s[8:9]
	s_cbranch_execz .LBB0_547
	s_waitcnt lgkmcnt(0)
	v_cvt_pk_bf16_f32 v10, v6, v7
	v_add_co_u32_e32 v6, vcc, 0x11000, v14
	s_nop 1
	v_addc_co_u32_e32 v7, vcc, 0, v15, vcc
	global_store_dword v[6:7], v10, off offset:64
.LBB0_547:
	s_or_b64 exec, exec, s[10:11]
	v_mul_f32_e32 v6, v59, v0
	s_waitcnt lgkmcnt(0)
	s_nop 1
	v_mov_b32_dpp v7, v6 quad_perm:[1,0,3,2] row_mask:0xf bank_mask:0xf
	s_and_saveexec_b64 s[10:11], s[8:9]
	s_cbranch_execz .LBB0_549
	s_waitcnt lgkmcnt(0)
	v_cvt_pk_bf16_f32 v10, v6, v7
	v_add_co_u32_e32 v6, vcc, 0x11000, v14
	s_nop 1
	v_addc_co_u32_e32 v7, vcc, 0, v15, vcc
	global_store_dword v[6:7], v10, off offset:128
.LBB0_549:
	s_or_b64 exec, exec, s[10:11]
	v_mul_f32_e32 v0, v25, v0
	s_nop 1
	v_mov_b32_dpp v6, v0 quad_perm:[1,0,3,2] row_mask:0xf bank_mask:0xf
	s_and_saveexec_b64 s[10:11], s[8:9]
	s_cbranch_execz .LBB0_551
	s_waitcnt lgkmcnt(0)
	v_cvt_pk_bf16_f32 v0, v0, v6
	v_add_co_u32_e32 v6, vcc, 0x11000, v14
	s_nop 1
	v_addc_co_u32_e32 v7, vcc, 0, v15, vcc
	global_store_dword v[6:7], v0, off offset:192
.LBB0_551:
	s_or_b64 exec, exec, s[10:11]
	v_rcp_f32_e32 v0, v8
	s_waitcnt lgkmcnt(0)
	v_mul_f32_e32 v6, v92, v0
	s_nop 1
	v_mov_b32_dpp v7, v6 quad_perm:[1,0,3,2] row_mask:0xf bank_mask:0xf
	s_and_saveexec_b64 s[10:11], s[8:9]
	s_cbranch_execz .LBB0_553
	s_waitcnt lgkmcnt(0)
	v_cvt_pk_bf16_f32 v8, v6, v7
	v_add_co_u32_e32 v6, vcc, 0x12000, v14
	s_nop 1
	v_addc_co_u32_e32 v7, vcc, 0, v15, vcc
	global_store_dword v[6:7], v8, off
.LBB0_553:
	s_or_b64 exec, exec, s[10:11]
	v_mul_f32_e32 v6, v76, v0
	s_waitcnt lgkmcnt(0)
	s_nop 1
	v_mov_b32_dpp v7, v6 quad_perm:[1,0,3,2] row_mask:0xf bank_mask:0xf
	s_and_saveexec_b64 s[10:11], s[8:9]
	s_cbranch_execz .LBB0_555
	s_waitcnt lgkmcnt(0)
	v_cvt_pk_bf16_f32 v8, v6, v7
	v_add_co_u32_e32 v6, vcc, 0x12000, v14
	s_nop 1
	v_addc_co_u32_e32 v7, vcc, 0, v15, vcc
	global_store_dword v[6:7], v8, off offset:64
.LBB0_555:
	s_or_b64 exec, exec, s[10:11]
	v_mul_f32_e32 v6, v60, v0
	s_waitcnt lgkmcnt(0)
	s_nop 1
	v_mov_b32_dpp v7, v6 quad_perm:[1,0,3,2] row_mask:0xf bank_mask:0xf
	s_and_saveexec_b64 s[10:11], s[8:9]
	s_cbranch_execz .LBB0_557
	s_waitcnt lgkmcnt(0)
	v_cvt_pk_bf16_f32 v8, v6, v7
	v_add_co_u32_e32 v6, vcc, 0x12000, v14
	s_nop 1
	v_addc_co_u32_e32 v7, vcc, 0, v15, vcc
	global_store_dword v[6:7], v8, off offset:128
.LBB0_557:
	s_or_b64 exec, exec, s[10:11]
	v_mul_f32_e32 v0, v26, v0
	s_nop 1
	v_mov_b32_dpp v6, v0 quad_perm:[1,0,3,2] row_mask:0xf bank_mask:0xf
	s_and_saveexec_b64 s[10:11], s[8:9]
	s_cbranch_execz .LBB0_559
	s_waitcnt lgkmcnt(0)
	v_cvt_pk_bf16_f32 v0, v0, v6
	v_add_co_u32_e32 v6, vcc, 0x12000, v14
	s_nop 1
	v_addc_co_u32_e32 v7, vcc, 0, v15, vcc
	global_store_dword v[6:7], v0, off offset:192
.LBB0_559:
	s_or_b64 exec, exec, s[10:11]
	v_rcp_f32_e32 v0, v9
	s_waitcnt lgkmcnt(0)
	v_mul_f32_e32 v6, v93, v0
	s_nop 1
	v_mov_b32_dpp v7, v6 quad_perm:[1,0,3,2] row_mask:0xf bank_mask:0xf
	s_and_saveexec_b64 s[10:11], s[8:9]
	s_cbranch_execz .LBB0_561
	s_waitcnt lgkmcnt(0)
	v_cvt_pk_bf16_f32 v8, v6, v7
	v_add_co_u32_e32 v6, vcc, 0x13000, v14
	s_nop 1
	v_addc_co_u32_e32 v7, vcc, 0, v15, vcc
	global_store_dword v[6:7], v8, off
.LBB0_561:
	s_or_b64 exec, exec, s[10:11]
	v_mul_f32_e32 v6, v77, v0
	s_waitcnt lgkmcnt(0)
	s_nop 1
	v_mov_b32_dpp v7, v6 quad_perm:[1,0,3,2] row_mask:0xf bank_mask:0xf
	s_and_saveexec_b64 s[10:11], s[8:9]
	s_cbranch_execz .LBB0_563
	s_waitcnt lgkmcnt(0)
	v_cvt_pk_bf16_f32 v8, v6, v7
	v_add_co_u32_e32 v6, vcc, 0x13000, v14
	s_nop 1
	v_addc_co_u32_e32 v7, vcc, 0, v15, vcc
	global_store_dword v[6:7], v8, off offset:64
.LBB0_563:
	s_or_b64 exec, exec, s[10:11]
	v_mul_f32_e32 v6, v61, v0
	s_waitcnt lgkmcnt(0)
	s_nop 1
	v_mov_b32_dpp v7, v6 quad_perm:[1,0,3,2] row_mask:0xf bank_mask:0xf
	s_and_saveexec_b64 s[10:11], s[8:9]
	s_cbranch_execz .LBB0_565
	s_waitcnt lgkmcnt(0)
	v_cvt_pk_bf16_f32 v8, v6, v7
	v_add_co_u32_e32 v6, vcc, 0x13000, v14
	s_nop 1
	v_addc_co_u32_e32 v7, vcc, 0, v15, vcc
	global_store_dword v[6:7], v8, off offset:128
.LBB0_565:
	s_or_b64 exec, exec, s[10:11]
	v_mul_f32_e32 v0, v27, v0
	s_nop 1
	v_mov_b32_dpp v6, v0 quad_perm:[1,0,3,2] row_mask:0xf bank_mask:0xf
	s_and_saveexec_b64 s[10:11], s[8:9]
	s_cbranch_execz .LBB0_567
	s_waitcnt lgkmcnt(0)
	v_cvt_pk_bf16_f32 v0, v0, v6
	v_add_co_u32_e32 v6, vcc, 0x13000, v14
	s_nop 1
	v_addc_co_u32_e32 v7, vcc, 0, v15, vcc
	global_store_dword v[6:7], v0, off offset:192
.LBB0_567:
	s_or_b64 exec, exec, s[10:11]
	v_rcp_f32_e32 v0, v2
	s_nop 0
	v_mul_f32_e32 v2, v94, v0
	s_waitcnt lgkmcnt(0)
	s_nop 1
	v_mov_b32_dpp v6, v2 quad_perm:[1,0,3,2] row_mask:0xf bank_mask:0xf
	s_and_saveexec_b64 s[10:11], s[8:9]
	s_cbranch_execz .LBB0_569
	s_waitcnt lgkmcnt(0)
	v_cvt_pk_bf16_f32 v2, v2, v6
	v_add_co_u32_e32 v6, vcc, 0x18000, v14
	s_nop 1
	v_addc_co_u32_e32 v7, vcc, 0, v15, vcc
	global_store_dword v[6:7], v2, off
.LBB0_569:
	s_or_b64 exec, exec, s[10:11]
	v_mul_f32_e32 v2, v78, v0
	s_waitcnt lgkmcnt(0)
	s_nop 1
	v_mov_b32_dpp v6, v2 quad_perm:[1,0,3,2] row_mask:0xf bank_mask:0xf
	s_and_saveexec_b64 s[10:11], s[8:9]
	s_cbranch_execz .LBB0_571
	s_waitcnt lgkmcnt(0)
	v_cvt_pk_bf16_f32 v2, v2, v6
	v_add_co_u32_e32 v6, vcc, 0x18000, v14
	s_nop 1
	v_addc_co_u32_e32 v7, vcc, 0, v15, vcc
	global_store_dword v[6:7], v2, off offset:64
.LBB0_571:
	s_or_b64 exec, exec, s[10:11]
	v_mul_f32_e32 v2, v62, v0
	s_waitcnt lgkmcnt(0)
	s_nop 1
	v_mov_b32_dpp v6, v2 quad_perm:[1,0,3,2] row_mask:0xf bank_mask:0xf
	s_and_saveexec_b64 s[10:11], s[8:9]
	s_cbranch_execz .LBB0_573
	s_waitcnt lgkmcnt(0)
	v_cvt_pk_bf16_f32 v2, v2, v6
	v_add_co_u32_e32 v6, vcc, 0x18000, v14
	s_nop 1
	v_addc_co_u32_e32 v7, vcc, 0, v15, vcc
	global_store_dword v[6:7], v2, off offset:128
.LBB0_573:
	s_or_b64 exec, exec, s[10:11]
	v_mul_f32_e32 v0, v28, v0
	s_nop 1
	v_mov_b32_dpp v2, v0 quad_perm:[1,0,3,2] row_mask:0xf bank_mask:0xf
	s_and_saveexec_b64 s[10:11], s[8:9]
	s_cbranch_execz .LBB0_575
	s_waitcnt lgkmcnt(1)
	v_add_co_u32_e32 v6, vcc, 0x18000, v14
	s_waitcnt lgkmcnt(0)
	v_cvt_pk_bf16_f32 v0, v0, v2
	s_nop 0
	v_addc_co_u32_e32 v7, vcc, 0, v15, vcc
	global_store_dword v[6:7], v0, off offset:192
.LBB0_575:
	s_or_b64 exec, exec, s[10:11]
	v_rcp_f32_e32 v0, v3
	s_waitcnt lgkmcnt(0)
	v_mul_f32_e32 v2, v95, v0
	s_nop 1
	v_mov_b32_dpp v3, v2 quad_perm:[1,0,3,2] row_mask:0xf bank_mask:0xf
	s_and_saveexec_b64 s[10:11], s[8:9]
	s_cbranch_execz .LBB0_577
	s_waitcnt lgkmcnt(0)
	v_cvt_pk_bf16_f32 v6, v2, v3
	v_add_co_u32_e32 v2, vcc, 0x19000, v14
	s_nop 1
	v_addc_co_u32_e32 v3, vcc, 0, v15, vcc
	global_store_dword v[2:3], v6, off
.LBB0_577:
	s_or_b64 exec, exec, s[10:11]
	v_mul_f32_e32 v2, v79, v0
	s_waitcnt lgkmcnt(0)
	s_nop 1
	v_mov_b32_dpp v3, v2 quad_perm:[1,0,3,2] row_mask:0xf bank_mask:0xf
	s_and_saveexec_b64 s[10:11], s[8:9]
	s_cbranch_execz .LBB0_579
	s_waitcnt lgkmcnt(0)
	v_cvt_pk_bf16_f32 v6, v2, v3
	v_add_co_u32_e32 v2, vcc, 0x19000, v14
	s_nop 1
	v_addc_co_u32_e32 v3, vcc, 0, v15, vcc
	global_store_dword v[2:3], v6, off offset:64
.LBB0_579:
	s_or_b64 exec, exec, s[10:11]
	v_mul_f32_e32 v2, v63, v0
	s_waitcnt lgkmcnt(0)
	s_nop 1
	v_mov_b32_dpp v3, v2 quad_perm:[1,0,3,2] row_mask:0xf bank_mask:0xf
	s_and_saveexec_b64 s[10:11], s[8:9]
	s_cbranch_execz .LBB0_581
	s_waitcnt lgkmcnt(0)
	v_cvt_pk_bf16_f32 v6, v2, v3
	v_add_co_u32_e32 v2, vcc, 0x19000, v14
	s_nop 1
	v_addc_co_u32_e32 v3, vcc, 0, v15, vcc
	global_store_dword v[2:3], v6, off offset:128
.LBB0_581:
	s_or_b64 exec, exec, s[10:11]
	v_mul_f32_e32 v0, v29, v0
	s_nop 1
	v_mov_b32_dpp v2, v0 quad_perm:[1,0,3,2] row_mask:0xf bank_mask:0xf
	s_and_saveexec_b64 s[10:11], s[8:9]
	s_cbranch_execz .LBB0_583
	s_waitcnt lgkmcnt(0)
	v_cvt_pk_bf16_f32 v0, v0, v2
	v_add_co_u32_e32 v2, vcc, 0x19000, v14
	s_nop 1
	v_addc_co_u32_e32 v3, vcc, 0, v15, vcc
	global_store_dword v[2:3], v0, off offset:192
.LBB0_583:
	s_or_b64 exec, exec, s[10:11]
	v_rcp_f32_e32 v0, v4
	s_waitcnt lgkmcnt(0)
	v_mul_f32_e32 v2, v96, v0
	s_nop 1
	v_mov_b32_dpp v3, v2 quad_perm:[1,0,3,2] row_mask:0xf bank_mask:0xf
	s_and_saveexec_b64 s[10:11], s[8:9]
	s_cbranch_execz .LBB0_585
	s_waitcnt lgkmcnt(0)
	v_cvt_pk_bf16_f32 v4, v2, v3
	v_add_co_u32_e32 v2, vcc, 0x1a000, v14
	s_nop 1
	v_addc_co_u32_e32 v3, vcc, 0, v15, vcc
	global_store_dword v[2:3], v4, off
.LBB0_585:
	s_or_b64 exec, exec, s[10:11]
	v_mul_f32_e32 v2, v80, v0
	s_waitcnt lgkmcnt(0)
	s_nop 1
	v_mov_b32_dpp v3, v2 quad_perm:[1,0,3,2] row_mask:0xf bank_mask:0xf
	s_and_saveexec_b64 s[10:11], s[8:9]
	s_cbranch_execz .LBB0_587
	s_waitcnt lgkmcnt(0)
	v_cvt_pk_bf16_f32 v4, v2, v3
	v_add_co_u32_e32 v2, vcc, 0x1a000, v14
	s_nop 1
	v_addc_co_u32_e32 v3, vcc, 0, v15, vcc
	global_store_dword v[2:3], v4, off offset:64
.LBB0_587:
	s_or_b64 exec, exec, s[10:11]
	v_mul_f32_e32 v2, v64, v0
	s_waitcnt lgkmcnt(0)
	s_nop 1
	v_mov_b32_dpp v3, v2 quad_perm:[1,0,3,2] row_mask:0xf bank_mask:0xf
	s_and_saveexec_b64 s[10:11], s[8:9]
	s_cbranch_execz .LBB0_589
	s_waitcnt lgkmcnt(0)
	v_cvt_pk_bf16_f32 v4, v2, v3
	v_add_co_u32_e32 v2, vcc, 0x1a000, v14
	s_nop 1
	v_addc_co_u32_e32 v3, vcc, 0, v15, vcc
	global_store_dword v[2:3], v4, off offset:128
.LBB0_589:
	s_or_b64 exec, exec, s[10:11]
	v_mul_f32_e32 v0, v30, v0
	s_nop 1
	v_mov_b32_dpp v2, v0 quad_perm:[1,0,3,2] row_mask:0xf bank_mask:0xf
	s_and_saveexec_b64 s[10:11], s[8:9]
	s_cbranch_execz .LBB0_591
	s_waitcnt lgkmcnt(0)
	v_cvt_pk_bf16_f32 v0, v0, v2
	v_add_co_u32_e32 v2, vcc, 0x1a000, v14
	s_nop 1
	v_addc_co_u32_e32 v3, vcc, 0, v15, vcc
	global_store_dword v[2:3], v0, off offset:192
.LBB0_591:
	s_or_b64 exec, exec, s[10:11]
	v_rcp_f32_e32 v0, v5
	s_waitcnt lgkmcnt(0)
	v_mul_f32_e32 v2, v97, v0
	s_nop 1
	v_mov_b32_dpp v3, v2 quad_perm:[1,0,3,2] row_mask:0xf bank_mask:0xf
	s_and_saveexec_b64 s[10:11], s[8:9]
	s_cbranch_execz .LBB0_593
	s_waitcnt lgkmcnt(0)
	v_cvt_pk_bf16_f32 v4, v2, v3
	v_add_co_u32_e32 v2, vcc, 0x1b000, v14
	s_nop 1
	v_addc_co_u32_e32 v3, vcc, 0, v15, vcc
	global_store_dword v[2:3], v4, off
.LBB0_593:
	s_or_b64 exec, exec, s[10:11]
	v_mul_f32_e32 v2, v81, v0
	s_waitcnt lgkmcnt(0)
	s_nop 1
	v_mov_b32_dpp v3, v2 quad_perm:[1,0,3,2] row_mask:0xf bank_mask:0xf
	s_and_saveexec_b64 s[10:11], s[8:9]
	s_cbranch_execz .LBB0_595
	s_waitcnt lgkmcnt(0)
	v_cvt_pk_bf16_f32 v4, v2, v3
	v_add_co_u32_e32 v2, vcc, 0x1b000, v14
	s_nop 1
	v_addc_co_u32_e32 v3, vcc, 0, v15, vcc
	global_store_dword v[2:3], v4, off offset:64
.LBB0_595:
	s_or_b64 exec, exec, s[10:11]
	v_mul_f32_e32 v2, v65, v0
	s_waitcnt lgkmcnt(0)
	s_nop 1
	v_mov_b32_dpp v3, v2 quad_perm:[1,0,3,2] row_mask:0xf bank_mask:0xf
	s_and_saveexec_b64 s[10:11], s[8:9]
	s_cbranch_execz .LBB0_597
	s_waitcnt lgkmcnt(0)
	v_cvt_pk_bf16_f32 v4, v2, v3
	v_add_co_u32_e32 v2, vcc, 0x1b000, v14
	s_nop 1
	v_addc_co_u32_e32 v3, vcc, 0, v15, vcc
	global_store_dword v[2:3], v4, off offset:128
.LBB0_597:
	s_or_b64 exec, exec, s[10:11]
	v_mul_f32_e32 v0, v31, v0
	s_nop 1
	v_mov_b32_dpp v2, v0 quad_perm:[1,0,3,2] row_mask:0xf bank_mask:0xf
	s_and_saveexec_b64 s[10:11], s[8:9]
	s_cbranch_execz .LBB0_406
	s_waitcnt lgkmcnt(0)
	v_cvt_pk_bf16_f32 v0, v0, v2
	v_add_co_u32_e32 v2, vcc, 0x1b000, v14
	s_nop 1
	v_addc_co_u32_e32 v3, vcc, 0, v15, vcc
	global_store_dword v[2:3], v0, off offset:192
	s_branch .LBB0_406
